# P8 small-tile GEMM: K-step-per-wave fragment mapping halves the LDS read traffic of the LDS-bound chunk loop (6 instead of 16 ds_read_b128 per wave and chunk), partial tiles reduced through LDS once p
# speedup vs baseline: 1.0136x; 1.0136x over previous
; #define LAS __attribute__((address_space(3)))
; #define SG_LOAD(kc, sg) do { _Pragma("unroll") for (int i_ = 0; i_ < 4; ++i_) { const int idx_ = tid + 512 * i_; \
;             ra[sg][i_] = *(const u32x4*)(A + (size_t)(row0 + (idx_ >> 5)) * ld + (kc) * 256 + (idx_ & 31) * 8); if (NC == 64 || i_ < 2) rb[sg][i_] = *(const u32x4*)(Bt + (size_t)(col0 + (idx_ >> 5)) * ld + (kc) * 256 + (idx_ & 31) * 8); } } while (0)
; template <int NC, class Epi>
; __device__ __forceinline__ void small_gemm_phase(LAS unsigned char* lds, const bf16_t* A, const bf16_t* Bt, int K, int ld, int ncolt  , const Epi& E, int first, int nblk, int bid, int tid) {
;     ...
;     for (int u = ub; u < 8 * ncolt; u += nblk) {
;         const int rt = u & 7, ct = u >> 3;
;         const int row0 = NPT + 64 * rt, col0 = NC * ct;
;         u32x4 ra[2][4], rb[2][4];
;     ...
;         SG_LOAD(0, 0); SG_LOAD(1, 1);
;         f32x4 acc0 = {0.f, 0.f, 0.f, 0.f}, acc1 = {0.f, 0.f, 0.f, 0.f};
;         const LAS unsigned char* apl = lds + (16 * mt + fr) * SG_STRIDE + 16 * fq;
;         const LAS unsigned char* bpl = lds + SG_BOFF + ((NC / 2) * nh + fr) * SG_STRIDE + 16 * fq;
; #pragma unroll 1
;         for (int kc = 0; kc < nch; kc += 2) { SG_STEP(kc, 0); SG_STEP(kc + 1, 1); }
.LBB0_1289:
	s_and_b32 s8, s13, 0x7fffffe0
	v_or_b32_e32 v52, s8, v95
	s_and_b32 s8, s18, 0x1c0
	v_lshlrev_b64 v[48:49], 13, v[52:53]
	v_add_lshl_u32 v52, v116, s8, 13
	v_lshl_add_u64 v[62:63], s[58:59], 0, v[52:53]
	v_add_lshl_u32 v52, v117, s8, 13
	v_lshl_add_u64 v[64:65], s[58:59], 0, v[52:53]
	v_add_lshl_u32 v52, v118, s8, 13
	v_lshl_add_u64 v[66:67], s[58:59], 0, v[52:53]
	v_add_lshl_u32 v52, v119, s8, 13
	s_lshl_b32 s8, s21, 6
	s_and_b32 s23, s8, 0x1c0
	s_bitset1_b32 s23, 14
	s_lshl_b32 s8, s21, 2
	v_or_b32_e32 v0, s23, v95
	v_lshl_add_u64 v[68:69], s[58:59], 0, v[52:53]
	s_and_b32 s22, s8, 0x7fffffe0
	v_lshlrev_b32_e32 v52, 13, v0
	v_lshl_add_u64 v[50:51], v[54:55], 0, v[52:53]
	v_or_b32_e32 v52, s22, v95
	v_lshlrev_b64 v[0:1], 13, v[52:53]
	v_lshl_add_u64 v[70:71], v[56:57], 0, v[0:1]
	v_or_b32_e32 v0, s23, v96
	v_lshlrev_b32_e32 v52, 13, v0
	v_lshl_add_u64 v[72:73], v[54:55], 0, v[52:53]
	v_add_u32_e32 v52, s22, v96
	v_lshlrev_b64 v[0:1], 13, v[52:53]
	v_lshl_add_u64 v[74:75], v[56:57], 0, v[0:1]
	v_or_b32_e32 v0, s23, v97
	v_lshlrev_b32_e32 v52, 13, v0
	v_lshl_add_u64 v[76:77], v[54:55], 0, v[52:53]
	v_add_lshl_u32 v52, s23, v98, 13
	v_lshl_add_u64 v[78:79], v[54:55], 0, v[52:53]
	global_load_dwordx4 v[0:3], v[50:51], off
	global_load_dwordx4 v[8:11], v[70:71], off
	global_load_dwordx4 v[16:19], v[72:73], off
	global_load_dwordx4 v[24:27], v[74:75], off
	global_load_dwordx4 v[32:35], v[76:77], off
	global_load_dwordx4 v[40:43], v[78:79], off
	global_load_dwordx4 v[4:7], v[50:51], off offset:512
	global_load_dwordx4 v[12:15], v[70:71], off offset:512
	global_load_dwordx4 v[20:23], v[72:73], off offset:512
	global_load_dwordx4 v[28:31], v[74:75], off offset:512
	global_load_dwordx4 v[36:39], v[76:77], off offset:512
	global_load_dwordx4 v[44:47], v[78:79], off offset:512
	s_bfe_u32 s8, s13, 0x1a0005
	s_lshl_b64 s[16:17], s[8:9], 18
	v_lshl_add_u64 v[70:71], v[60:61], 0, s[16:17]
	v_lshl_add_u64 v[72:73], s[58:59], 0, v[48:49]
	s_mov_b32 s8, 0
	v_mov_b32_e32 v48, 0
	v_mov_b32_e32 v49, v53
	v_mov_b32_e32 v50, v53
	v_mov_b32_e32 v51, v53
	v_and_b32_e32 v144, 15, v192
	v_mul_u32_u24_e32 v144, 0x210, v144
	v_bfe_u32 v145, v192, 4, 2
	v_lshl_add_u32 v144, v145, 4, v144
	v_lshrrev_b32_e32 v145, 6, v192
	v_lshl_add_u32 v144, v145, 6, v144
	v_add_u32_e32 v145, 0x10800, v144
	v_mov_b32_e32 v160, 0
	v_mov_b32_e32 v161, 0
	v_mov_b32_e32 v162, 0
	v_mov_b32_e32 v163, 0
	v_mov_b32_e32 v164, 0
	v_mov_b32_e32 v165, 0
	v_mov_b32_e32 v166, 0
	v_mov_b32_e32 v167, 0
	v_mov_b32_e32 v168, 0
	v_mov_b32_e32 v169, 0
	v_mov_b32_e32 v170, 0
	v_mov_b32_e32 v171, 0
	v_mov_b32_e32 v172, 0
	v_mov_b32_e32 v173, 0
	v_mov_b32_e32 v174, 0
	v_mov_b32_e32 v175, 0
	v_mov_b32_e32 v176, 0
	v_mov_b32_e32 v177, 0
	v_mov_b32_e32 v178, 0
	v_mov_b32_e32 v179, 0
	v_mov_b32_e32 v180, 0
	v_mov_b32_e32 v181, 0
	v_mov_b32_e32 v182, 0
	v_mov_b32_e32 v183, 0
	v_mov_b32_e32 v184, 0
	v_mov_b32_e32 v185, 0
	v_mov_b32_e32 v186, 0
	v_mov_b32_e32 v187, 0
	v_mov_b32_e32 v188, 0
	v_mov_b32_e32 v189, 0
	v_mov_b32_e32 v190, 0
	v_mov_b32_e32 v191, 0
	s_branch .LBB0_1291
.LBB0_1290:
	s_waitcnt lgkmcnt(0)
	s_barrier
	ds_read_b128 v[194:197], v145
	ds_read_b128 v[198:201], v145 offset:8448
	ds_read_b128 v[202:205], v145 offset:16896
	ds_read_b128 v[206:209], v145 offset:25344
	ds_read_b128 v[210:213], v145 offset:33792
	ds_read_b128 v[214:217], v145 offset:42240
	s_waitcnt lgkmcnt(0)
	v_mfma_f32_16x16x32_bf16 v[160:163], v[210:213], v[194:197], v[160:163]
	v_mfma_f32_16x16x32_bf16 v[164:167], v[214:217], v[194:197], v[164:167]
	v_mfma_f32_16x16x32_bf16 v[168:171], v[210:213], v[198:201], v[168:171]
	v_mfma_f32_16x16x32_bf16 v[172:175], v[214:217], v[198:201], v[172:175]
	v_mfma_f32_16x16x32_bf16 v[176:179], v[210:213], v[202:205], v[176:179]
	v_mfma_f32_16x16x32_bf16 v[180:183], v[214:217], v[202:205], v[180:183]
	v_mfma_f32_16x16x32_bf16 v[184:187], v[210:213], v[206:209], v[184:187]
	v_mfma_f32_16x16x32_bf16 v[188:191], v[214:217], v[206:209], v[188:191]
	s_add_i32 s8, s8, 2
	v_lshl_add_u64 v[70:71], v[70:71], 0, s[10:11]
	v_lshl_add_u64 v[72:73], v[72:73], 0, s[10:11]
	v_lshl_add_u64 v[62:63], v[62:63], 0, s[10:11]
	v_lshl_add_u64 v[64:65], v[64:65], 0, s[10:11]
	v_lshl_add_u64 v[66:67], v[66:67], 0, s[10:11]
	v_lshl_add_u64 v[68:69], v[68:69], 0, s[10:11]
	s_and_b64 vcc, exec, s[16:17]
	s_cbranch_vccnz .Lsk_p8_reduce

.LBB0_1293:
	s_waitcnt lgkmcnt(0)
	s_barrier
	ds_read_b128 v[194:197], v144
	ds_read_b128 v[198:201], v144 offset:8448
	ds_read_b128 v[202:205], v144 offset:16896
	ds_read_b128 v[206:209], v144 offset:25344
	ds_read_b128 v[210:213], v144 offset:33792
	ds_read_b128 v[214:217], v144 offset:42240
	s_waitcnt lgkmcnt(0)
	v_mfma_f32_16x16x32_bf16 v[160:163], v[210:213], v[194:197], v[160:163]
	v_mfma_f32_16x16x32_bf16 v[164:167], v[214:217], v[194:197], v[164:167]
	v_mfma_f32_16x16x32_bf16 v[168:171], v[210:213], v[198:201], v[168:171]
	v_mfma_f32_16x16x32_bf16 v[172:175], v[214:217], v[198:201], v[172:175]
	v_mfma_f32_16x16x32_bf16 v[176:179], v[210:213], v[202:205], v[176:179]
	v_mfma_f32_16x16x32_bf16 v[180:183], v[214:217], v[202:205], v[180:183]
	v_mfma_f32_16x16x32_bf16 v[184:187], v[210:213], v[206:209], v[184:187]
	v_mfma_f32_16x16x32_bf16 v[188:191], v[214:217], v[206:209], v[188:191]
	v_add_u32_e32 v52, v90, v99
	s_cmp_gt_u32 s8, 12
	s_waitcnt vmcnt(11)
	ds_write_b128 v52, v[4:7]
	v_add_u32_e32 v128, v91, v99
	s_waitcnt vmcnt(10)
	ds_write_b128 v128, v[12:15]
	v_add_u32_e32 v124, v90, v100
	s_waitcnt vmcnt(9)
	ds_write_b128 v124, v[20:23]
	v_add_u32_e32 v124, v91, v100
	s_waitcnt vmcnt(8)
	ds_write_b128 v124, v[28:31]
	s_waitcnt vmcnt(7)
	ds_write_b128 v52, v[36:39] offset:16896
	v_add_u32_e32 v52, v90, v101
	s_waitcnt vmcnt(6)
	ds_write_b128 v52, v[44:47]
	s_cbranch_scc1 .LBB0_1290
	v_add_co_u32_e32 v4, vcc, 0x2c00000, v84
	s_nop 1
	v_addc_co_u32_e32 v5, vcc, 0, v85, vcc
	v_add_co_u32_e32 v12, vcc, 0x1700000, v82
	global_load_dwordx4 v[4:7], v[4:5], off offset:1536
	s_nop 0
	v_addc_co_u32_e32 v13, vcc, 0, v83, vcc
	v_add_co_u32_e32 v20, vcc, 0x2c00000, v80
	global_load_dwordx4 v[12:15], v[12:13], off offset:1536
	s_nop 0
	v_addc_co_u32_e32 v21, vcc, 0, v81, vcc
	v_add_co_u32_e32 v28, vcc, 0x1700000, v78
	global_load_dwordx4 v[20:23], v[20:21], off offset:1536
	s_nop 0
	v_addc_co_u32_e32 v29, vcc, 0, v79, vcc
	v_add_co_u32_e32 v36, vcc, 0x2c00000, v76
	global_load_dwordx4 v[28:31], v[28:29], off offset:1536
	s_nop 0
	v_addc_co_u32_e32 v37, vcc, 0, v77, vcc
	v_add_co_u32_e32 v44, vcc, 0x2c00000, v74
	global_load_dwordx4 v[36:39], v[36:37], off offset:1536
	s_nop 0
	v_addc_co_u32_e32 v45, vcc, 0, v75, vcc
	global_load_dwordx4 v[44:47], v[44:45], off offset:1536
	s_branch .LBB0_1290

; #define LAS __attribute__((address_space(3)))
; #define SG_LOAD(kc, sg) do { _Pragma("unroll") for (int i_ = 0; i_ < 4; ++i_) { const int idx_ = tid + 512 * i_; \
;             ra[sg][i_] = *(const u32x4*)(A + (size_t)(row0 + (idx_ >> 5)) * ld + (kc) * 256 + (idx_ & 31) * 8); if (NC == 64 || i_ < 2) rb[sg][i_] = *(const u32x4*)(Bt + (size_t)(col0 + (idx_ >> 5)) * ld + (kc) * 256 + (idx_ & 31) * 8); } } while (0)
; template <int NC, class Epi>
; __device__ __forceinline__ void small_gemm_phase(LAS unsigned char* lds, const bf16_t* A, const bf16_t* Bt, int K, int ld, int ncolt  , const Epi& E, int first, int nblk, int bid, int tid) {
;     ...
;         SG_LOAD(0, 0); SG_LOAD(1, 1);
;         f32x4 acc0 = {0.f, 0.f, 0.f, 0.f}, acc1 = {0.f, 0.f, 0.f, 0.f};
;         const LAS unsigned char* apl = lds + (16 * mt + fr) * SG_STRIDE + 16 * fq;
;         const LAS unsigned char* bpl = lds + SG_BOFF + ((NC / 2) * nh + fr) * SG_STRIDE + 16 * fq;
; #pragma unroll 1
;         for (int kc = 0; kc < nch; kc += 2) { SG_STEP(kc, 0); SG_STEP(kc + 1, 1); }
;     ...
;         E(row0 + 16 * mt + fr, col0 + (NC / 2) * nh, fq, acc0, acc1, NC == 64 ? 2 : 1);
.Lsk_p8_reduce:
	s_nop 15
	s_nop 15
	s_waitcnt lgkmcnt(0)
	s_barrier
	v_lshlrev_b32_e32 v146, 4, v192
	v_lshrrev_b32_e32 v147, 6, v192
	v_mul_u32_u24_e32 v147, 0x1c00, v147
	v_add_u32_e32 v147, v146, v147
	ds_write_b128 v147, v[160:163]
	ds_write_b128 v147, v[164:167] offset:1024
	ds_write_b128 v147, v[168:171] offset:2048
	ds_write_b128 v147, v[172:175] offset:3072
	ds_write_b128 v147, v[176:179] offset:4096
	ds_write_b128 v147, v[180:183] offset:5120
	ds_write_b128 v147, v[184:187] offset:6144
	ds_write_b128 v147, v[188:191] offset:7168
	s_waitcnt lgkmcnt(0)
	s_barrier
	ds_read_b128 v[194:197], v146
	ds_read_b128 v[198:201], v146 offset:8192
	ds_read_b128 v[202:205], v146 offset:16384
	ds_read_b128 v[206:209], v146 offset:24576
	ds_read_b128 v[210:213], v146 offset:32768
	ds_read_b128 v[214:217], v146 offset:40960
	ds_read_b128 v[218:221], v146 offset:49152
	ds_read_b128 v[222:225], v146 offset:57344
	s_waitcnt lgkmcnt(6)
	v_pk_add_f32 v[48:49], v[194:195], v[198:199]
	v_pk_add_f32 v[50:51], v[196:197], v[200:201]
	s_waitcnt lgkmcnt(5)
	v_pk_add_f32 v[48:49], v[48:49], v[202:203]
	v_pk_add_f32 v[50:51], v[50:51], v[204:205]
	s_waitcnt lgkmcnt(4)
	v_pk_add_f32 v[48:49], v[48:49], v[206:207]
	v_pk_add_f32 v[50:51], v[50:51], v[208:209]
	s_waitcnt lgkmcnt(3)
	v_pk_add_f32 v[48:49], v[48:49], v[210:211]
	v_pk_add_f32 v[50:51], v[50:51], v[212:213]
	s_waitcnt lgkmcnt(2)
	v_pk_add_f32 v[48:49], v[48:49], v[214:215]
	v_pk_add_f32 v[50:51], v[50:51], v[216:217]
	s_waitcnt lgkmcnt(1)
	v_pk_add_f32 v[48:49], v[48:49], v[218:219]
	v_pk_add_f32 v[50:51], v[50:51], v[220:221]
	s_waitcnt lgkmcnt(0)
	v_pk_add_f32 v[48:49], v[48:49], v[222:223]
	v_pk_add_f32 v[50:51], v[50:51], v[224:225]
	s_barrier
	s_branch .LBB0_1288
